# v58 + 9216 more FFN2 gate conversion items moved from the P7 tail into P4's idle tail round (TAIL_GU 12288->21504); helper flag poll interval doubled
# baseline (speedup 1.0000x reference)
.LBB0_405:
	s_cmpk_gt_i32 s7, 0x53ff
	s_cbranch_scc1 .LBB0_415
	s_sub_i32 s8, 0x53ff, s7
	s_mul_hi_i32 s8, s8, 0x2aaaaaab
	s_lshr_b32 s9, s8, 31
	s_lshr_b32 s8, s8, 8
	s_add_i32 s24, s8, s9
	s_mulk_i32 s24, 0x600
	s_cmp_lt_i32 s24, 0
	s_cbranch_scc1 .LBB0_415
	s_mul_hi_i32 s9, s7, 0x2fa0be83
	s_lshr_b32 s10, s9, 31
	s_ashr_i32 s9, s9, 6
	v_readlane_b32 s36, v254, 7
	v_lshrrev_b32_e32 v134, 3, v134
	s_add_i32 s12, s9, s10
	v_readlane_b32 s37, v254, 8
	s_waitcnt vmcnt(23)
	v_lshl_or_b32 v2, s12, 6, v134
	s_mov_b32 s9, 0xac00
	s_waitcnt vmcnt(14)
	v_mov_b64_e32 v[66:67], s[36:37]
	v_mad_i64_i32 v[2:3], s[10:11], v2, s9, v[66:67]
	s_mul_i32 s10, s12, 0xfffffea8
	s_add_i32 s10, s10, s7
	s_lshl_b32 s10, s10, 5
	v_and_b32_e32 v1, 7, v1
	s_ashr_i32 s11, s10, 31
	v_mov_b32_e32 v131, 0
	v_lshl_add_u64 v[2:3], s[10:11], 2, v[2:3]
	v_lshlrev_b32_e32 v130, 4, v1
	v_lshl_add_u64 v[26:27], v[2:3], 0, v[130:131]
	s_mov_b32 s10, 0x56000
	s_add_i32 s8, s24, s7
	v_add_co_u32_e32 v6, vcc, s10, v26
	s_add_i32 s25, s7, 0xc00
	s_nop 0
	v_addc_co_u32_e32 v7, vcc, 0, v27, vcc
	s_mov_b32 s11, 0xac000
	s_cmpk_gt_u32 s24, 0xc00
	v_add_co_u32_e32 v10, vcc, s11, v26
	s_cselect_b32 s26, s25, s8
	s_nop 0
	v_addc_co_u32_e32 v11, vcc, 0, v27, vcc
	s_mov_b32 s12, 0x102000
	s_mul_hi_i32 s24, s26, 0x2fa0be83
	v_add_co_u32_e32 v14, vcc, s12, v26
	s_lshr_b32 s25, s24, 31
	s_ashr_i32 s24, s24, 6
	v_addc_co_u32_e32 v15, vcc, 0, v27, vcc
	s_mov_b32 s13, 0x158000
	s_add_i32 s27, s24, s25
	v_add_co_u32_e32 v18, vcc, s13, v26
	s_waitcnt vmcnt(2)
	v_lshl_or_b32 v34, s27, 6, v134
	v_addc_co_u32_e32 v19, vcc, 0, v27, vcc
	s_mov_b32 s15, 0x1ae000
	v_mad_i64_i32 v[34:35], s[24:25], v34, s9, v[66:67]
	v_add_co_u32_e32 v22, vcc, s15, v26
	s_mul_i32 s24, s27, 0xfffffea8
	s_nop 0
	v_addc_co_u32_e32 v23, vcc, 0, v27, vcc
	s_mov_b32 s22, 0x204000
	s_add_i32 s24, s24, s26
	v_add_co_u32_e32 v28, vcc, s22, v26
	s_lshl_b32 s24, s24, 5
	s_nop 0
	v_addc_co_u32_e32 v29, vcc, 0, v27, vcc
	s_mov_b32 s23, 0x25a000
	s_ashr_i32 s25, s24, 31
	v_add_co_u32_e32 v30, vcc, s23, v26
	v_lshl_add_u64 v[34:35], s[24:25], 2, v[34:35]
	s_nop 0
	v_addc_co_u32_e32 v31, vcc, 0, v27, vcc
	v_lshl_add_u64 v[46:47], v[34:35], 0, v[130:131]
	v_add_co_u32_e32 v48, vcc, s23, v46
	s_addk_i32 s7, 0x600
	s_nop 0
	v_addc_co_u32_e32 v49, vcc, 0, v47, vcc
	v_add_co_u32_e32 v34, vcc, s22, v46
	s_min_i32 s7, s7, s8
	s_nop 0
	v_addc_co_u32_e32 v35, vcc, 0, v47, vcc
	s_mul_hi_i32 s24, s7, 0x2fa0be83
	v_add_co_u32_e32 v36, vcc, s15, v46
	s_lshr_b32 s25, s24, 31
	s_ashr_i32 s24, s24, 6
	v_addc_co_u32_e32 v37, vcc, 0, v47, vcc
	s_add_i32 s26, s24, s25
	v_add_co_u32_e32 v38, vcc, s13, v46
	v_lshl_or_b32 v68, s26, 6, v134
	s_nop 0
	v_addc_co_u32_e32 v39, vcc, 0, v47, vcc
	v_mad_i64_i32 v[66:67], s[24:25], v68, s9, v[66:67]
	v_add_co_u32_e32 v40, vcc, s12, v46
	s_mul_i32 s24, s26, 0xfffffea8
	s_nop 0
	v_addc_co_u32_e32 v41, vcc, 0, v47, vcc
	s_add_i32 s24, s24, s7
	v_add_co_u32_e32 v42, vcc, s11, v46
	s_lshl_b32 s24, s24, 5
	s_nop 0
	v_addc_co_u32_e32 v43, vcc, 0, v47, vcc
	s_ashr_i32 s25, s24, 31
	v_add_co_u32_e32 v44, vcc, s10, v46
	v_lshl_add_u64 v[66:67], s[24:25], 2, v[66:67]
	s_nop 0
	v_addc_co_u32_e32 v45, vcc, 0, v47, vcc
	v_lshl_add_u64 v[78:79], v[66:67], 0, v[130:131]
	v_add_co_u32_e32 v80, vcc, s23, v78
	global_load_dwordx4 v[2:5], v[26:27], off
	s_nop 0
	global_load_dwordx4 v[6:9], v[6:7], off
	v_addc_co_u32_e32 v81, vcc, 0, v79, vcc
	v_add_co_u32_e32 v66, vcc, s22, v78
	global_load_dwordx4 v[10:13], v[10:11], off
	s_nop 0
	global_load_dwordx4 v[14:17], v[14:15], off
	v_addc_co_u32_e32 v67, vcc, 0, v79, vcc
	v_add_co_u32_e32 v68, vcc, s15, v78
	global_load_dwordx4 v[18:21], v[18:19], off
	s_nop 0
	global_load_dwordx4 v[22:25], v[22:23], off
	v_addc_co_u32_e32 v69, vcc, 0, v79, vcc
	global_load_dwordx4 v[26:29], v[28:29], off
	s_nop 0
	global_load_dwordx4 v[30:33], v[30:31], off
	s_nop 0
	global_load_dwordx4 v[50:53], v[34:35], off
	s_nop 0
	global_load_dwordx4 v[34:37], v[36:37], off
	s_nop 0
	global_load_dwordx4 v[54:57], v[38:39], off
	s_nop 0
	global_load_dwordx4 v[38:41], v[40:41], off
	s_nop 0
	global_load_dwordx4 v[58:61], v[42:43], off
	s_nop 0
	global_load_dwordx4 v[42:45], v[44:45], off
	s_nop 0
	global_load_dwordx4 v[62:65], v[48:49], off
	s_nop 0
	global_load_dwordx4 v[46:49], v[46:47], off
	s_nop 0
	global_load_dwordx4 v[90:93], v[66:67], off
	global_load_dwordx4 v[74:77], v[68:69], off
	v_add_co_u32_e32 v66, vcc, s13, v78
	v_mul_u32_u24_e32 v100, 0x420, v1
	s_nop 0
	v_addc_co_u32_e32 v67, vcc, 0, v79, vcc
	v_add_co_u32_e32 v68, vcc, s12, v78
	v_lshlrev_b32_e32 v102, 2, v134
	s_nop 0
	v_addc_co_u32_e32 v69, vcc, 0, v79, vcc
	global_load_dwordx4 v[86:89], v[66:67], off
	global_load_dwordx4 v[70:73], v[68:69], off
	v_add_co_u32_e32 v66, vcc, s11, v78
	v_add_u32_e32 v99, s6, v130
	s_nop 0
	v_addc_co_u32_e32 v67, vcc, 0, v79, vcc
	v_add_co_u32_e32 v68, vcc, s10, v78
	v_readlane_b32 s24, v255, 13
	s_nop 0
	v_addc_co_u32_e32 v69, vcc, 0, v79, vcc
	global_load_dwordx4 v[82:85], v[66:67], off
	s_nop 0
	global_load_dwordx4 v[66:69], v[68:69], off
	s_nop 0
	global_load_dwordx4 v[94:97], v[80:81], off
	s_nop 0
	global_load_dwordx4 v[78:81], v[78:79], off
	v_add3_u32 v137, s6, v100, v102
	s_lshl_b32 s6, s2, 9
	s_lshl_b32 s7, s0, 6
	v_lshlrev_b32_e32 v98, 2, v1
	v_readlane_b32 s25, v255, 14
	v_mul_u32_u24_e32 v101, 0x84, v134
	s_add_i32 s6, s6, s7
	s_lshl_b32 s7, s2, 8
	s_lshl_b32 s0, s0, 5
	v_lshl_add_u64 v[132:133], s[24:25], 0, v[130:131]
	v_or_b32_e32 v1, 8, v134
	v_or_b32_e32 v135, 16, v134
	v_or_b32_e32 v136, 24, v134
	s_addk_i32 s1, 0x2200
	s_add_i32 s0, s7, s0
	v_lshlrev_b32_e32 v130, 2, v98
	v_add_u32_e32 v138, v99, v101
	v_readlane_b32 s38, v254, 9
	v_readlane_b32 s39, v254, 10
	v_readlane_b32 s40, v254, 11
	v_readlane_b32 s41, v254, 12
	v_readlane_b32 s42, v254, 13
	v_readlane_b32 s43, v254, 14
	s_branch .LBB0_409

.Lhflag_4:
	ds_read_b32 v249, v246
	s_waitcnt lgkmcnt(0)
	v_cmp_gt_u32_e32 vcc, s64, v249
	s_nop 0
	s_cbranch_vccz .Lhflag_go_4
	s_sleep 12
	s_branch .Lhflag_4

.LBB0_1053:
	s_cmpk_lg_i32 s33, 0x100
	s_cbranch_scc1 .Lcv_done
	s_cmpk_lt_i32 s2, 0x80
	s_cbranch_scc1 .Lcv_done
	v_readfirstlane_b32 s4, v0
	v_and_b32_e32 v1, 63, v0
	s_lshr_b32 s4, s4, 6
	s_sub_i32 s5, s2, 0x80
	s_lshl_b32 s5, s5, 3
	s_add_i32 s5, s5, s4
	v_lshrrev_b32_e32 v2, 3, v1
	v_and_b32_e32 v3, 7, v1
	s_lshl_b32 s6, s4, 14
	v_mul_u32_u24_e32 v4, 33, v2
	v_lshl_add_u32 v4, v3, 2, v4
	v_lshl_add_u32 v4, v4, 2, s6
	v_mul_u32_u24_e32 v5, 0x108, v3
	v_add_u32_e32 v5, v5, v2
	v_lshl_add_u32 v5, v5, 2, s6
	v_lshlrev_b32_e32 v78, 4, v3
	v_readlane_b32 s8, v254, 7
	v_readlane_b32 s9, v254, 8
	v_readlane_b32 s10, v254, 9
	v_readlane_b32 s11, v254, 10
	v_readlane_b32 s12, v254, 11
	v_readlane_b32 s13, v254, 12
	s_add_u32 s14, s92, 0x4b800000
	s_addc_u32 s15, s93, 0
	s_add_u32 s36, s92, 0x10300000
	s_addc_u32 s37, s93, 0
	s_mov_b32 s38, 0
	s_cmp_lt_u32 s5, 0x200
	s_movk_i32 s7, 0x2c00
	s_cselect_b32 s7, 0x3000, s7
	s_add_i32 s7, s7, s5
	s_add_i32 s7, s7, 0xd000
	s_cmp_lt_u32 s38, 22
	s_cbranch_scc0 .Lcv_dec_d0
	s_lshl_b32 s39, s38, 10
	s_add_i32 s39, s39, s5
	s_add_i32 s39, s39, 0x5400
	s_mov_b32 s58, 1
	s_cmp_ge_u32 s39, 0x5600
	s_cselect_b32 s43, 0x5600, 0
	s_cselect_b32 s40, s10, s8
	s_cselect_b32 s41, s11, s9
	s_cselect_b32 s42, 0x80, 0
	s_sub_i32 s39, s39, s43
	s_mul_hi_u32 s43, s39, 0x2fa0be83
	s_lshr_b32 s43, s43, 6
	s_mul_i32 s44, s43, 0x158
	s_sub_i32 s44, s39, s44
	s_lshl_b32 s45, s43, 6
	s_lshl_b32 s46, s44, 5
	s_mul_i32 s47, s45, 0x2b00
	s_add_i32 s47, s47, s46
	s_lshl_b32 s47, s47, 2
	s_add_u32 s40, s40, s47
	s_addc_u32 s41, s41, 0
	s_lshr_b32 s48, s46, 7
	s_lshl_b32 s48, s48, 8
	s_and_b32 s49, s46, 0x7f
	s_add_i32 s48, s48, s49
	s_add_i32 s48, s48, s42
	s_lshl_b32 s48, s48, 12
	s_add_i32 s48, s48, s45
	s_lshl_b32 s48, s48, 1
	s_add_u32 s50, s14, s48
	s_addc_u32 s51, s15, 0
	s_mov_b32 s53, 0x56000
	s_mov_b32 s52, 0x10000
	s_mov_b32 s57, 0xac00
	s_movk_i32 s47, 0x2000
	s_branch .Lcv_dec_e0
.Lcv_dec_d0:
	s_sub_i32 s39, s38, 22
	s_lshl_b32 s39, s39, 10
	s_add_i32 s39, s39, s5
	s_add_i32 s39, s39, 0xd000
	s_cmp_le_u32 s39, s7
	s_cselect_b32 s58, 1, 0
	s_min_u32 s39, s39, s7
	s_sub_i32 s39, s39, 0xac00
	s_lshr_b32 s43, s39, 7
	s_and_b32 s44, s39, 0x7f
	s_lshl_b32 s45, s43, 6
	s_lshl_b32 s46, s44, 5
	s_lshl_b32 s47, s45, 12
	s_add_i32 s47, s47, s46
	s_lshl_b32 s47, s47, 2
	s_add_u32 s40, s12, s47
	s_addc_u32 s41, s13, 0
	s_mul_i32 s48, s46, 0x2b00
	s_add_i32 s48, s48, s45
	s_lshl_b32 s48, s48, 1
	s_add_u32 s50, s36, s48
	s_addc_u32 s51, s37, 0
	s_mov_b32 s53, 0x20000
	s_mov_b32 s52, 0x2b000
	s_movk_i32 s57, 0x4000
	s_movk_i32 s47, 0x5600
.Lcv_dec_e0:
	v_mad_u32_u24 v75, v2, s57, v78
	v_mad_u32_u24 v76, v2, s47, v78
	s_addk_i32 s38, 1
	global_load_dwordx4 v[10:13], v75, s[40:41]
	s_add_u32 s40, s40, s53
	s_addc_u32 s41, s41, 0
	global_load_dwordx4 v[14:17], v75, s[40:41]
	s_add_u32 s40, s40, s53
	s_addc_u32 s41, s41, 0
	global_load_dwordx4 v[18:21], v75, s[40:41]
	s_add_u32 s40, s40, s53
	s_addc_u32 s41, s41, 0
	global_load_dwordx4 v[22:25], v75, s[40:41]
	s_add_u32 s40, s40, s53
	s_addc_u32 s41, s41, 0
	global_load_dwordx4 v[26:29], v75, s[40:41]
	s_add_u32 s40, s40, s53
	s_addc_u32 s41, s41, 0
	global_load_dwordx4 v[30:33], v75, s[40:41]
	s_add_u32 s40, s40, s53
	s_addc_u32 s41, s41, 0
	global_load_dwordx4 v[34:37], v75, s[40:41]
	s_add_u32 s40, s40, s53
	s_addc_u32 s41, s41, 0
	global_load_dwordx4 v[38:41], v75, s[40:41]
	s_cmp_lt_u32 s38, 22
	s_cbranch_scc0 .Lcv_dec_d1
	s_lshl_b32 s39, s38, 10
	s_add_i32 s39, s39, s5
	s_add_i32 s39, s39, 0x5400
	s_mov_b32 s59, 1
	s_cmp_ge_u32 s39, 0x5600
	s_cselect_b32 s43, 0x5600, 0
	s_cselect_b32 s40, s10, s8
	s_cselect_b32 s41, s11, s9
	s_cselect_b32 s42, 0x80, 0
	s_sub_i32 s39, s39, s43
	s_mul_hi_u32 s43, s39, 0x2fa0be83
	s_lshr_b32 s43, s43, 6
	s_mul_i32 s44, s43, 0x158
	s_sub_i32 s44, s39, s44
	s_lshl_b32 s45, s43, 6
	s_lshl_b32 s46, s44, 5
	s_mul_i32 s47, s45, 0x2b00
	s_add_i32 s47, s47, s46
	s_lshl_b32 s47, s47, 2
	s_add_u32 s40, s40, s47
	s_addc_u32 s41, s41, 0
	s_lshr_b32 s48, s46, 7
	s_lshl_b32 s48, s48, 8
	s_and_b32 s49, s46, 0x7f
	s_add_i32 s48, s48, s49
	s_add_i32 s48, s48, s42
	s_lshl_b32 s48, s48, 12
	s_add_i32 s48, s48, s45
	s_lshl_b32 s48, s48, 1
	s_add_u32 s54, s14, s48
	s_addc_u32 s55, s15, 0
	s_mov_b32 s53, 0x56000
	s_mov_b32 s56, 0x10000
	s_mov_b32 s57, 0xac00
	s_movk_i32 s47, 0x2000
	s_branch .Lcv_dec_e1
.Lcv_dec_d1:
	s_sub_i32 s39, s38, 22
	s_lshl_b32 s39, s39, 10
	s_add_i32 s39, s39, s5
	s_add_i32 s39, s39, 0xd000
	s_cmp_le_u32 s39, s7
	s_cselect_b32 s59, 1, 0
	s_min_u32 s39, s39, s7
	s_sub_i32 s39, s39, 0xac00
	s_lshr_b32 s43, s39, 7
	s_and_b32 s44, s39, 0x7f
	s_lshl_b32 s45, s43, 6
	s_lshl_b32 s46, s44, 5
	s_lshl_b32 s47, s45, 12
	s_add_i32 s47, s47, s46
	s_lshl_b32 s47, s47, 2
	s_add_u32 s40, s12, s47
	s_addc_u32 s41, s13, 0
	s_mul_i32 s48, s46, 0x2b00
	s_add_i32 s48, s48, s45
	s_lshl_b32 s48, s48, 1
	s_add_u32 s54, s36, s48
	s_addc_u32 s55, s37, 0
	s_mov_b32 s53, 0x20000
	s_mov_b32 s56, 0x2b000
	s_movk_i32 s57, 0x4000
	s_movk_i32 s47, 0x5600

.Lcv_loop:
	v_mov_b32_e32 v74, v4
	ds_write2_b32 v74, v10, v11 offset1:1
	ds_write2_b32 v74, v12, v13 offset0:2 offset1:3
	v_add_u32_e32 v74, 0x420, v74
	ds_write2_b32 v74, v14, v15 offset1:1
	ds_write2_b32 v74, v16, v17 offset0:2 offset1:3
	v_add_u32_e32 v74, 0x420, v74
	ds_write2_b32 v74, v18, v19 offset1:1
	ds_write2_b32 v74, v20, v21 offset0:2 offset1:3
	v_add_u32_e32 v74, 0x420, v74
	ds_write2_b32 v74, v22, v23 offset1:1
	ds_write2_b32 v74, v24, v25 offset0:2 offset1:3
	v_add_u32_e32 v74, 0x420, v74
	ds_write2_b32 v74, v26, v27 offset1:1
	ds_write2_b32 v74, v28, v29 offset0:2 offset1:3
	v_add_u32_e32 v74, 0x420, v74
	ds_write2_b32 v74, v30, v31 offset1:1
	ds_write2_b32 v74, v32, v33 offset0:2 offset1:3
	v_add_u32_e32 v74, 0x420, v74
	ds_write2_b32 v74, v34, v35 offset1:1
	ds_write2_b32 v74, v36, v37 offset0:2 offset1:3
	v_add_u32_e32 v74, 0x420, v74
	ds_write2_b32 v74, v38, v39 offset1:1
	ds_write2_b32 v74, v40, v41 offset0:2 offset1:3
	s_waitcnt lgkmcnt(0)
	ds_read2_b32 v[42:43], v5 offset0:0 offset1:33
	ds_read2_b32 v[44:45], v5 offset0:66 offset1:99
	ds_read2_b32 v[46:47], v5 offset0:132 offset1:165
	ds_read2_b32 v[48:49], v5 offset0:198 offset1:231
	ds_read2_b32 v[50:51], v5 offset0:8 offset1:41
	ds_read2_b32 v[52:53], v5 offset0:74 offset1:107
	ds_read2_b32 v[54:55], v5 offset0:140 offset1:173
	ds_read2_b32 v[56:57], v5 offset0:206 offset1:239
	ds_read2_b32 v[58:59], v5 offset0:16 offset1:49
	ds_read2_b32 v[60:61], v5 offset0:82 offset1:115
	ds_read2_b32 v[62:63], v5 offset0:148 offset1:181
	ds_read2_b32 v[64:65], v5 offset0:214 offset1:247
	ds_read2_b32 v[66:67], v5 offset0:24 offset1:57
	ds_read2_b32 v[68:69], v5 offset0:90 offset1:123
	ds_read2_b32 v[70:71], v5 offset0:156 offset1:189
	ds_read2_b32 v[72:73], v5 offset0:222 offset1:255
	s_waitcnt lgkmcnt(0)
	v_cvt_pk_bf16_f32 v112, v42, v43
	v_cvt_pk_bf16_f32 v113, v44, v45
	v_cvt_pk_bf16_f32 v114, v46, v47
	v_cvt_pk_bf16_f32 v115, v48, v49
	v_cvt_pk_bf16_f32 v116, v50, v51
	v_cvt_pk_bf16_f32 v117, v52, v53
	v_cvt_pk_bf16_f32 v118, v54, v55
	v_cvt_pk_bf16_f32 v119, v56, v57
	v_cvt_pk_bf16_f32 v120, v58, v59
	v_cvt_pk_bf16_f32 v121, v60, v61
	v_cvt_pk_bf16_f32 v122, v62, v63
	v_cvt_pk_bf16_f32 v123, v64, v65
	v_cvt_pk_bf16_f32 v124, v66, v67
	v_cvt_pk_bf16_f32 v125, v68, v69
	v_cvt_pk_bf16_f32 v126, v70, v71
	v_cvt_pk_bf16_f32 v127, v72, v73
	s_nop 1
	global_store_dwordx4 v76, v[112:115], s[50:51]
	s_add_u32 s50, s50, s52
	s_addc_u32 s51, s51, 0
	global_store_dwordx4 v76, v[116:119], s[50:51]
	s_add_u32 s50, s50, s52
	s_addc_u32 s51, s51, 0
	global_store_dwordx4 v76, v[120:123], s[50:51]
	s_add_u32 s50, s50, s52
	s_addc_u32 s51, s51, 0
	global_store_dwordx4 v76, v[124:127], s[50:51]
	s_cmp_lt_u32 s38, 22
	s_cbranch_scc0 .Lcv_dec_d2
	s_lshl_b32 s39, s38, 10
	s_add_i32 s39, s39, s5
	s_add_i32 s39, s39, 0x5400
	s_mov_b32 s58, 1
	s_cmp_ge_u32 s39, 0x5600
	s_cselect_b32 s43, 0x5600, 0
	s_cselect_b32 s40, s10, s8
	s_cselect_b32 s41, s11, s9
	s_cselect_b32 s42, 0x80, 0
	s_sub_i32 s39, s39, s43
	s_mul_hi_u32 s43, s39, 0x2fa0be83
	s_lshr_b32 s43, s43, 6
	s_mul_i32 s44, s43, 0x158
	s_sub_i32 s44, s39, s44
	s_lshl_b32 s45, s43, 6
	s_lshl_b32 s46, s44, 5
	s_mul_i32 s47, s45, 0x2b00
	s_add_i32 s47, s47, s46
	s_lshl_b32 s47, s47, 2
	s_add_u32 s40, s40, s47
	s_addc_u32 s41, s41, 0
	s_lshr_b32 s48, s46, 7
	s_lshl_b32 s48, s48, 8
	s_and_b32 s49, s46, 0x7f
	s_add_i32 s48, s48, s49
	s_add_i32 s48, s48, s42
	s_lshl_b32 s48, s48, 12
	s_add_i32 s48, s48, s45
	s_lshl_b32 s48, s48, 1
	s_add_u32 s50, s14, s48
	s_addc_u32 s51, s15, 0
	s_mov_b32 s53, 0x56000
	s_mov_b32 s52, 0x10000
	s_mov_b32 s57, 0xac00
	s_movk_i32 s47, 0x2000
	s_branch .Lcv_dec_e2

.Lcv_dec_e2:
	v_mad_u32_u24 v75, v2, s57, v78
	v_mad_u32_u24 v76, v2, s47, v78
	s_addk_i32 s38, 1
	global_load_dwordx4 v[10:13], v75, s[40:41]
	s_add_u32 s40, s40, s53
	s_addc_u32 s41, s41, 0
	global_load_dwordx4 v[14:17], v75, s[40:41]
	s_add_u32 s40, s40, s53
	s_addc_u32 s41, s41, 0
	global_load_dwordx4 v[18:21], v75, s[40:41]
	s_add_u32 s40, s40, s53
	s_addc_u32 s41, s41, 0
	global_load_dwordx4 v[22:25], v75, s[40:41]
	s_add_u32 s40, s40, s53
	s_addc_u32 s41, s41, 0
	global_load_dwordx4 v[26:29], v75, s[40:41]
	s_add_u32 s40, s40, s53
	s_addc_u32 s41, s41, 0
	global_load_dwordx4 v[30:33], v75, s[40:41]
	s_add_u32 s40, s40, s53
	s_addc_u32 s41, s41, 0
	global_load_dwordx4 v[34:37], v75, s[40:41]
	s_add_u32 s40, s40, s53
	s_addc_u32 s41, s41, 0
	global_load_dwordx4 v[38:41], v75, s[40:41]
	s_waitcnt vmcnt(12)
	s_cmp_eq_u32 s59, 0
	s_cbranch_scc1 .Lcv_done
	v_mov_b32_e32 v74, v4
	ds_write2_b32 v74, v80, v81 offset1:1
	ds_write2_b32 v74, v82, v83 offset0:2 offset1:3
	v_add_u32_e32 v74, 0x420, v74
	ds_write2_b32 v74, v84, v85 offset1:1
	ds_write2_b32 v74, v86, v87 offset0:2 offset1:3
	v_add_u32_e32 v74, 0x420, v74
	ds_write2_b32 v74, v88, v89 offset1:1
	ds_write2_b32 v74, v90, v91 offset0:2 offset1:3
	v_add_u32_e32 v74, 0x420, v74
	ds_write2_b32 v74, v92, v93 offset1:1
	ds_write2_b32 v74, v94, v95 offset0:2 offset1:3
	v_add_u32_e32 v74, 0x420, v74
	ds_write2_b32 v74, v96, v97 offset1:1
	ds_write2_b32 v74, v98, v99 offset0:2 offset1:3
	v_add_u32_e32 v74, 0x420, v74
	ds_write2_b32 v74, v100, v101 offset1:1
	ds_write2_b32 v74, v102, v103 offset0:2 offset1:3
	v_add_u32_e32 v74, 0x420, v74
	ds_write2_b32 v74, v104, v105 offset1:1
	ds_write2_b32 v74, v106, v107 offset0:2 offset1:3
	v_add_u32_e32 v74, 0x420, v74
	ds_write2_b32 v74, v108, v109 offset1:1
	ds_write2_b32 v74, v110, v111 offset0:2 offset1:3
	s_waitcnt lgkmcnt(0)
	ds_read2_b32 v[42:43], v5 offset0:0 offset1:33
	ds_read2_b32 v[44:45], v5 offset0:66 offset1:99
	ds_read2_b32 v[46:47], v5 offset0:132 offset1:165
	ds_read2_b32 v[48:49], v5 offset0:198 offset1:231
	ds_read2_b32 v[50:51], v5 offset0:8 offset1:41
	ds_read2_b32 v[52:53], v5 offset0:74 offset1:107
	ds_read2_b32 v[54:55], v5 offset0:140 offset1:173
	ds_read2_b32 v[56:57], v5 offset0:206 offset1:239
	ds_read2_b32 v[58:59], v5 offset0:16 offset1:49
	ds_read2_b32 v[60:61], v5 offset0:82 offset1:115
	ds_read2_b32 v[62:63], v5 offset0:148 offset1:181
	ds_read2_b32 v[64:65], v5 offset0:214 offset1:247
	ds_read2_b32 v[66:67], v5 offset0:24 offset1:57
	ds_read2_b32 v[68:69], v5 offset0:90 offset1:123
	ds_read2_b32 v[70:71], v5 offset0:156 offset1:189
	ds_read2_b32 v[72:73], v5 offset0:222 offset1:255
	s_waitcnt lgkmcnt(0)
	v_cvt_pk_bf16_f32 v112, v42, v43
	v_cvt_pk_bf16_f32 v113, v44, v45
	v_cvt_pk_bf16_f32 v114, v46, v47
	v_cvt_pk_bf16_f32 v115, v48, v49
	v_cvt_pk_bf16_f32 v116, v50, v51
	v_cvt_pk_bf16_f32 v117, v52, v53
	v_cvt_pk_bf16_f32 v118, v54, v55
	v_cvt_pk_bf16_f32 v119, v56, v57
	v_cvt_pk_bf16_f32 v120, v58, v59
	v_cvt_pk_bf16_f32 v121, v60, v61
	v_cvt_pk_bf16_f32 v122, v62, v63
	v_cvt_pk_bf16_f32 v123, v64, v65
	v_cvt_pk_bf16_f32 v124, v66, v67
	v_cvt_pk_bf16_f32 v125, v68, v69
	v_cvt_pk_bf16_f32 v126, v70, v71
	v_cvt_pk_bf16_f32 v127, v72, v73
	s_nop 1
	global_store_dwordx4 v77, v[112:115], s[54:55]
	s_add_u32 s54, s54, s56
	s_addc_u32 s55, s55, 0
	global_store_dwordx4 v77, v[116:119], s[54:55]
	s_add_u32 s54, s54, s56
	s_addc_u32 s55, s55, 0
	global_store_dwordx4 v77, v[120:123], s[54:55]
	s_add_u32 s54, s54, s56
	s_addc_u32 s55, s55, 0
	global_store_dwordx4 v77, v[124:127], s[54:55]
	s_cmp_lt_u32 s38, 22
	s_cbranch_scc0 .Lcv_dec_d3
	s_lshl_b32 s39, s38, 10
	s_add_i32 s39, s39, s5
	s_add_i32 s39, s39, 0x5400
	s_mov_b32 s59, 1
	s_cmp_ge_u32 s39, 0x5600
	s_cselect_b32 s43, 0x5600, 0
	s_cselect_b32 s40, s10, s8
	s_cselect_b32 s41, s11, s9
	s_cselect_b32 s42, 0x80, 0
	s_sub_i32 s39, s39, s43
	s_mul_hi_u32 s43, s39, 0x2fa0be83
	s_lshr_b32 s43, s43, 6
	s_mul_i32 s44, s43, 0x158
	s_sub_i32 s44, s39, s44
	s_lshl_b32 s45, s43, 6
	s_lshl_b32 s46, s44, 5
	s_mul_i32 s47, s45, 0x2b00
	s_add_i32 s47, s47, s46
	s_lshl_b32 s47, s47, 2
	s_add_u32 s40, s40, s47
	s_addc_u32 s41, s41, 0
	s_lshr_b32 s48, s46, 7
	s_lshl_b32 s48, s48, 8
	s_and_b32 s49, s46, 0x7f
	s_add_i32 s48, s48, s49
	s_add_i32 s48, s48, s42
	s_lshl_b32 s48, s48, 12
	s_add_i32 s48, s48, s45
	s_lshl_b32 s48, s48, 1
	s_add_u32 s54, s14, s48
	s_addc_u32 s55, s15, 0
	s_mov_b32 s53, 0x56000
	s_mov_b32 s56, 0x10000
	s_mov_b32 s57, 0xac00
	s_movk_i32 s47, 0x2000
	s_branch .Lcv_dec_e3
